# residual GEMM phases: context part-K unit processed between the two latent tiles (de-phases the halves' HBM-bound epilogues)
# baseline (speedup 1.0000x reference)
.LBB0_498:
	s_add_i32 s55, s55, 1
	s_mov_b32 s25, s55
	s_cmpk_lg_u32 s18, 0x100
	s_cbranch_scc1 .Lres_noswap
	s_cmpk_lt_i32 s34, 0x201
	s_cbranch_scc1 .Lres_noswap
	s_cmpk_gt_i32 s20, 0x7f
	s_cbranch_scc1 .Lres_noswap
	s_sub_i32 s21, 3, s55
	s_add_i32 s73, s55, -1
	s_cmp_lt_u32 s73, 2
	s_cselect_b32 s25, s21, s55
.Lres_noswap:
	s_mul_i32 s25, s25, s18
	s_add_i32 s25, s25, s20
	s_cmpk_lt_i32 s25, 0x200
	s_cselect_b64 s[38:39], -1, 0
	s_cmpk_gt_i32 s25, 0x1ff
	s_cselect_b64 s[2:3], -1, 0
	s_and_b64 s[78:79], s[2:3], exec
	s_cselect_b32 s21, 0, s25
	s_ashr_i32 s73, s21, 31
	s_lshr_b32 s73, s73, 29
	s_add_i32 s93, s21, s73
	s_and_b32 s73, s93, -8
	s_sub_i32 s73, s21, s73
	s_cmp_gt_i32 s73, -1
	s_mov_b64 s[78:79], -1
	s_cbranch_scc0 .LBB0_500
	s_lshl_b32 s21, s73, 6
	s_mov_b64 s[78:79], 0

.Ltr_low:
	s_mov_b32 s3, s20
	s_movk_i32 s9, 0x1900
	s_sub_i32 s2, s18, s2
